# down-weight transpose loop (select phase) counted waits: current item processed without waiting on the next item's just-issued loads
# baseline (speedup 1.0000x reference)
.LBB0_1179:
	s_and_b64 vcc, exec, s[0:1]
	s_cbranch_vccz .LBB0_1185
	s_add_i32 s10, s80, 0xffffff00
	s_cmpk_gt_i32 s10, 0x57ff
	s_cbranch_scc1 .LBB0_1185
	v_readlane_b32 s0, v253, 43
	s_waitcnt vmcnt(0)
	v_ashrrev_i32_e32 v68, 5, v80
	s_lshl_b32 s0, s0, 14
	v_ashrrev_i32_e32 v69, 31, v68
	s_add_i32 s4, s0, 0
	v_lshlrev_b64 v[2:3], 12, v[68:69]
	s_mov_b64 s[0:1], 0x2000
	v_lshl_add_u64 v[4:5], v[2:3], 0, s[0:1]
	s_mov_b64 s[0:1], 0x4000
	v_lshl_add_u64 v[6:7], v[2:3], 0, s[0:1]
	s_mov_b64 s[0:1], 0x6000
	v_lshl_add_u64 v[8:9], v[2:3], 0, s[0:1]
	s_mov_b64 s[0:1], 0x8000
	v_lshl_add_u64 v[10:11], v[2:3], 0, s[0:1]
	s_mov_b64 s[0:1], 0xa000
	v_lshl_add_u64 v[12:13], v[2:3], 0, s[0:1]
	s_mov_b64 s[0:1], 0xc000
	v_lshl_add_u64 v[14:15], v[2:3], 0, s[0:1]
	s_mov_b64 s[0:1], 0xe000
	v_lshl_add_u64 v[16:17], v[2:3], 0, s[0:1]
	s_mov_b64 s[0:1], 0x10000
	v_lshl_add_u64 v[18:19], v[2:3], 0, s[0:1]
	s_mov_b64 s[0:1], 0x12000
	v_lshl_add_u64 v[20:21], v[2:3], 0, s[0:1]
	s_mov_b64 s[0:1], 0x14000
	v_lshl_add_u64 v[22:23], v[2:3], 0, s[0:1]
	s_mov_b64 s[0:1], 0x16000
	v_lshl_add_u64 v[24:25], v[2:3], 0, s[0:1]
	s_mov_b64 s[0:1], 0x18000
	v_lshl_add_u64 v[26:27], v[2:3], 0, s[0:1]
	s_mov_b64 s[0:1], 0x1a000
	v_lshl_add_u64 v[28:29], v[2:3], 0, s[0:1]
	s_mov_b64 s[0:1], 0x1c000
	v_lshl_add_u64 v[30:31], v[2:3], 0, s[0:1]
	s_mov_b64 s[0:1], 0x1e000
	v_lshl_add_u64 v[32:33], v[2:3], 0, s[0:1]
	s_mov_b64 s[0:1], 0x20000
	v_lshl_add_u64 v[34:35], v[2:3], 0, s[0:1]
	s_mov_b64 s[0:1], 0x22000
	v_lshl_add_u64 v[36:37], v[2:3], 0, s[0:1]
	s_mov_b64 s[0:1], 0x24000
	v_lshl_add_u64 v[38:39], v[2:3], 0, s[0:1]
	s_mov_b64 s[0:1], 0x26000
	v_lshl_add_u64 v[40:41], v[2:3], 0, s[0:1]
	s_mov_b64 s[0:1], 0x28000
	v_lshl_add_u64 v[42:43], v[2:3], 0, s[0:1]
	s_mov_b64 s[0:1], 0x2a000
	v_lshl_add_u64 v[44:45], v[2:3], 0, s[0:1]
	s_mov_b64 s[0:1], 0x2c000
	v_lshl_add_u64 v[46:47], v[2:3], 0, s[0:1]
	s_mov_b64 s[0:1], 0x2e000
	v_lshl_add_u64 v[48:49], v[2:3], 0, s[0:1]
	s_mov_b64 s[0:1], 0x30000
	v_lshl_add_u64 v[50:51], v[2:3], 0, s[0:1]
	s_mov_b64 s[0:1], 0x32000
	v_lshl_add_u64 v[52:53], v[2:3], 0, s[0:1]
	s_mov_b64 s[0:1], 0x34000
	v_lshl_add_u64 v[54:55], v[2:3], 0, s[0:1]
	s_mov_b64 s[0:1], 0x36000
	v_lshl_add_u64 v[56:57], v[2:3], 0, s[0:1]
	s_mov_b64 s[0:1], 0x38000
	v_lshl_add_u64 v[58:59], v[2:3], 0, s[0:1]
	s_mov_b64 s[0:1], 0x3a000
	v_lshl_add_u64 v[60:61], v[2:3], 0, s[0:1]
	s_mov_b64 s[0:1], 0x3c000
	v_lshl_add_u64 v[62:63], v[2:3], 0, s[0:1]
	s_mov_b64 s[0:1], 0x3e000
	v_lshl_add_u64 v[64:65], v[2:3], 0, s[0:1]
	s_mul_hi_i32 s0, s10, 0x2e8ba2e9
	s_lshr_b32 s1, s0, 31
	s_ashr_i32 s0, s0, 8
	s_add_i32 s5, s0, s1
	s_mul_i32 s0, s5, 0x580
	s_sub_i32 s0, s10, s0
	s_sext_i32_i16 s1, s0
	s_bfe_u32 s1, s1, 0x5001a
	s_add_i32 s1, s0, s1
	s_sext_i32_i16 s7, s1
	s_and_b32 s1, s1, 0xffe0
	s_sub_i32 s0, s0, s1
	s_sext_i32_i16 s0, s0
	s_lshl_b32 s6, s0, 5
	s_lshl_b32 s0, s5, 10
	s_add_i32 s0, s6, s0
	s_add_i32 s11, s78, 0xffffff00
	s_mul_hi_i32 s1, s0, 0xb00
	s_mulk_i32 s0, 0xb00
	s_add_u32 s0, s96, s0
	s_addc_u32 s1, s97, s1
	s_lshl_b32 s7, s7, 1
	s_and_b32 s8, s7, 0xffffffc0
	s_ashr_i32 s9, s8, 31
	v_readlane_b32 s12, v253, 18
	s_add_u32 s0, s0, s8
	v_readlane_b32 s14, v253, 20
	v_readlane_b32 s15, v253, 21
	v_readlane_b32 s26, v253, 32
	v_readlane_b32 s27, v253, 33
	s_addc_u32 s1, s1, s9
	s_mul_hi_i32 s7, s5, 0xb00000
	s_mul_i32 s5, s5, 0xb00000
	s_mov_b64 s[14:15], s[26:27]
	s_add_u32 s5, s14, s5
	s_addc_u32 s7, s15, s7
	s_lshl_b64 s[8:9], s[8:9], 12
	s_add_u32 s5, s5, s8
	s_addc_u32 s8, s7, s9
	s_ashr_i32 s7, s6, 31
	s_lshl_b64 s[6:7], s[6:7], 2
	v_and_b32_e32 v76, 31, v80
	s_add_u32 s6, s5, s6
	v_mov_b32_e32 v1, 0
	s_addc_u32 s7, s8, s7
	v_lshlrev_b32_e32 v0, 2, v76
	v_lshl_add_u64 v[66:67], s[6:7], 0, v[0:1]
	v_lshl_add_u64 v[70:71], v[66:67], 0, v[2:3]
	v_lshl_add_u64 v[72:73], v[66:67], 0, v[4:5]
	v_lshl_add_u64 v[74:75], v[66:67], 0, v[6:7]
	v_lshl_add_u64 v[88:89], v[66:67], 0, v[8:9]
	v_lshl_add_u64 v[90:91], v[66:67], 0, v[10:11]
	v_lshl_add_u64 v[92:93], v[66:67], 0, v[12:13]
	v_lshl_add_u64 v[94:95], v[66:67], 0, v[14:15]
	v_lshl_add_u64 v[96:97], v[66:67], 0, v[16:17]
	global_load_dword v78, v[70:71], off
	global_load_dword v81, v[72:73], off
	global_load_dword v79, v[74:75], off
	global_load_dword v82, v[88:89], off
	global_load_dword v83, v[90:91], off
	global_load_dword v85, v[92:93], off
	global_load_dword v84, v[94:95], off
	global_load_dword v86, v[96:97], off
	v_lshl_add_u64 v[70:71], v[66:67], 0, v[18:19]
	v_lshl_add_u64 v[72:73], v[66:67], 0, v[20:21]
	v_lshl_add_u64 v[74:75], v[66:67], 0, v[22:23]
	v_lshl_add_u64 v[96:97], v[66:67], 0, v[24:25]
	v_lshl_add_u64 v[98:99], v[66:67], 0, v[26:27]
	v_lshl_add_u64 v[100:101], v[66:67], 0, v[28:29]
	v_lshl_add_u64 v[102:103], v[66:67], 0, v[30:31]
	v_lshl_add_u64 v[104:105], v[66:67], 0, v[32:33]
	global_load_dword v87, v[70:71], off
	global_load_dword v89, v[72:73], off
	global_load_dword v88, v[74:75], off
	global_load_dword v90, v[96:97], off
	global_load_dword v91, v[98:99], off
	global_load_dword v93, v[100:101], off
	global_load_dword v92, v[102:103], off
	global_load_dword v94, v[104:105], off
	v_lshl_add_u64 v[70:71], v[66:67], 0, v[34:35]
	v_lshl_add_u64 v[72:73], v[66:67], 0, v[36:37]
	v_lshl_add_u64 v[74:75], v[66:67], 0, v[38:39]
	v_lshl_add_u64 v[104:105], v[66:67], 0, v[40:41]
	v_lshl_add_u64 v[106:107], v[66:67], 0, v[42:43]
	v_lshl_add_u64 v[108:109], v[66:67], 0, v[44:45]
	v_lshl_add_u64 v[110:111], v[66:67], 0, v[46:47]
	v_lshl_add_u64 v[112:113], v[66:67], 0, v[48:49]
	global_load_dword v95, v[70:71], off
	global_load_dword v97, v[72:73], off
	global_load_dword v96, v[74:75], off
	global_load_dword v98, v[104:105], off
	global_load_dword v99, v[106:107], off
	global_load_dword v101, v[108:109], off
	global_load_dword v100, v[110:111], off
	global_load_dword v102, v[112:113], off
	v_lshl_add_u64 v[70:71], v[66:67], 0, v[50:51]
	v_lshl_add_u64 v[72:73], v[66:67], 0, v[52:53]
	v_lshl_add_u64 v[74:75], v[66:67], 0, v[54:55]
	v_lshl_add_u64 v[104:105], v[66:67], 0, v[56:57]
	v_lshl_add_u64 v[106:107], v[66:67], 0, v[58:59]
	v_lshl_add_u64 v[108:109], v[66:67], 0, v[60:61]
	v_lshl_add_u64 v[118:119], v[66:67], 0, v[62:63]
	v_lshl_add_u64 v[66:67], v[66:67], 0, v[64:65]
	global_load_dword v110, v[70:71], off
	global_load_dword v112, v[72:73], off
	global_load_dword v111, v[74:75], off
	global_load_dword v113, v[104:105], off
	global_load_dword v114, v[106:107], off
	global_load_dword v116, v[108:109], off
	global_load_dword v115, v[118:119], off
	global_load_dword v117, v[66:67], off
	v_lshlrev_b32_e32 v66, 3, v80
	v_add_u32_e32 v103, s4, v0
	v_ashrrev_i32_e32 v0, 3, v80
	v_and_b32_e32 v66, 56, v66
	s_movk_i32 s5, 0x84
	s_movk_i32 s6, 0xb00
	v_mul_u32_u24_e32 v69, 0x84, v66
	v_mul_lo_u32 v80, v68, s5
	v_lshlrev_b32_e32 v68, 2, v0
	v_add3_u32 v77, s4, v69, v68
	v_mad_i64_i32 v[68:69], s[4:5], v0, s6, 0
	v_add_u32_e32 v70, 8, v0
	v_add_u32_e32 v72, 16, v0
	v_add_u32_e32 v0, 24, v0
	v_mad_i64_i32 v[70:71], s[4:5], v70, s6, 0
	v_mad_i64_i32 v[72:73], s[4:5], v72, s6, 0
	v_mad_i64_i32 v[74:75], s[4:5], v0, s6, 0
	v_mov_b32_e32 v67, v1
	v_lshlrev_b32_e32 v0, 2, v76
	v_add_u32_e32 v76, v103, v80
	s_mov_b64 s[4:5], s[0:1]
	v_readlane_b32 s13, v253, 19
	v_readlane_b32 s16, v253, 22
	v_readlane_b32 s17, v253, 23
	v_readlane_b32 s18, v253, 24
	v_readlane_b32 s19, v253, 25
	v_readlane_b32 s20, v253, 26
	v_readlane_b32 s21, v253, 27
	v_readlane_b32 s22, v253, 28
	v_readlane_b32 s23, v253, 29
	v_readlane_b32 s24, v253, 30
	v_readlane_b32 s25, v253, 31
	s_waitcnt vmcnt(0)
	s_branch .LBB0_1183
.LBB0_1182:
	v_mul_f32_e32 v78, 0x42800000, v78
	v_mul_f32_e32 v81, 0x42800000, v81
	v_add_u32_e32 v142, 0x1000, v76
	ds_write2_b32 v142, v78, v81 offset1:66
	v_mul_f32_e32 v78, 0x42800000, v79
	v_mul_f32_e32 v79, 0x42800000, v82
	ds_write2_b32 v142, v78, v79 offset0:132 offset1:198
	v_mul_f32_e32 v78, 0x42800000, v83
	v_mul_f32_e32 v79, 0x42800000, v85
	v_add_u32_e32 v81, 0x1400, v76
	ds_write2_b32 v81, v78, v79 offset0:8 offset1:74
	v_mul_f32_e32 v78, 0x42800000, v84
	v_mul_f32_e32 v79, 0x42800000, v86
	ds_write2_b32 v81, v78, v79 offset0:140 offset1:206
	v_mul_f32_e32 v78, 0x42800000, v87
	v_mul_f32_e32 v79, 0x42800000, v89
	v_add_u32_e32 v81, 0x1800, v76
	ds_write2_b32 v81, v78, v79 offset0:16 offset1:82
	v_mul_f32_e32 v78, 0x42800000, v88
	v_mul_f32_e32 v79, 0x42800000, v90
	ds_write2_b32 v81, v78, v79 offset0:148 offset1:214
	v_mul_f32_e32 v78, 0x42800000, v91
	v_mul_f32_e32 v79, 0x42800000, v93
	v_add_u32_e32 v81, 0x1c00, v76
	ds_write2_b32 v81, v78, v79 offset0:24 offset1:90
	v_mul_f32_e32 v78, 0x42800000, v92
	v_mul_f32_e32 v79, 0x42800000, v94
	ds_write2_b32 v81, v78, v79 offset0:156 offset1:222
	v_mul_f32_e32 v78, 0x42800000, v95
	v_mul_f32_e32 v79, 0x42800000, v97
	v_add_u32_e32 v81, 0x2000, v76
	ds_write2_b32 v81, v78, v79 offset0:32 offset1:98
	v_mul_f32_e32 v78, 0x42800000, v96
	v_mul_f32_e32 v79, 0x42800000, v98
	ds_write2_b32 v81, v78, v79 offset0:164 offset1:230
	v_mul_f32_e32 v78, 0x42800000, v99
	v_mul_f32_e32 v79, 0x42800000, v101
	v_add_u32_e32 v81, 0x2400, v76
	ds_write2_b32 v81, v78, v79 offset0:40 offset1:106
	v_mul_f32_e32 v78, 0x42800000, v100
	v_mul_f32_e32 v79, 0x42800000, v102
	ds_write2_b32 v81, v78, v79 offset0:172 offset1:238
	v_mul_f32_e32 v78, 0x42800000, v110
	v_mul_f32_e32 v79, 0x42800000, v112
	v_add_u32_e32 v81, 0x2800, v76
	ds_write2_b32 v81, v78, v79 offset0:48 offset1:114
	v_mul_f32_e32 v78, 0x42800000, v111
	v_mul_f32_e32 v79, 0x42800000, v113
	ds_write2_b32 v81, v78, v79 offset0:180 offset1:246
	v_mul_f32_e32 v78, 0x42800000, v114
	v_mul_f32_e32 v79, 0x42800000, v116
	v_add_u32_e32 v81, 0x2c00, v76
	ds_write2_b32 v81, v78, v79 offset0:56 offset1:122
	v_mul_f32_e32 v78, 0x42800000, v115
	v_mul_f32_e32 v79, 0x42800000, v117
	ds_write2_b32 v81, v78, v79 offset0:188 offset1:254
	s_waitcnt lgkmcnt(0)
	v_add_u32_e32 v81, 0x1000, v77
	ds_read2_b32 v[82:83], v81 offset0:33 offset1:41
	ds_read2_b32 v[84:85], v81 offset0:66 offset1:74
	ds_read2_b32 v[86:87], v81 offset1:8
	ds_read2_b32 v[88:89], v81 offset0:99 offset1:107
	ds_read2_b32 v[92:93], v81 offset0:132 offset1:140
	ds_read2_b32 v[94:95], v81 offset0:165 offset1:173
	v_mov_b32_e32 v90, 0
	ds_read2_b32 v[96:97], v81 offset0:198 offset1:206
	ds_read2_b32 v[98:99], v81 offset0:231 offset1:239
	s_waitcnt lgkmcnt(5)
	v_cvt_pk_fp8_f32 v90, v86, v82
	v_mov_b32_e32 v91, 0
	v_mov_b32_e32 v82, 0
	s_waitcnt lgkmcnt(2)
	v_cvt_pk_fp8_f32 v91, v92, v94
	v_cvt_pk_fp8_f32 v82, v87, v83
	v_mov_b32_e32 v83, 0
	v_cvt_pk_fp8_f32 v83, v93, v95
	v_cvt_pk_fp8_f32 v90, v84, v88 op_sel:[0,0,1]
	s_waitcnt lgkmcnt(0)
	v_cvt_pk_fp8_f32 v91, v96, v98 op_sel:[0,0,1]
	v_cvt_pk_fp8_f32 v82, v85, v89 op_sel:[0,0,1]
	v_cvt_pk_fp8_f32 v83, v97, v99 op_sel:[0,0,1]
	v_lshl_add_u64 v[78:79], s[0:1], 0, v[66:67]
	v_lshl_add_u64 v[84:85], v[78:79], 0, v[68:69]
	global_store_dwordx2 v[84:85], v[90:91], off
	v_lshl_add_u64 v[84:85], v[78:79], 0, v[70:71]
	global_store_dwordx2 v[84:85], v[82:83], off
	ds_read2_b32 v[82:83], v81 offset0:49 offset1:57
	ds_read2_b32 v[84:85], v81 offset0:82 offset1:90
	ds_read2_b32 v[86:87], v81 offset0:16 offset1:24
	ds_read2_b32 v[88:89], v81 offset0:115 offset1:123
	ds_read2_b32 v[92:93], v81 offset0:148 offset1:156
	ds_read2_b32 v[94:95], v81 offset0:181 offset1:189
	v_mov_b32_e32 v90, 0
	ds_read2_b32 v[96:97], v81 offset0:214 offset1:222
	ds_read2_b32 v[98:99], v81 offset0:247 offset1:255
	s_waitcnt lgkmcnt(5)
	v_cvt_pk_fp8_f32 v90, v86, v82
	v_mov_b32_e32 v82, 0
	v_mov_b32_e32 v91, 0
	v_cvt_pk_fp8_f32 v82, v87, v83
	v_mov_b32_e32 v83, 0
	s_waitcnt lgkmcnt(2)
	v_cvt_pk_fp8_f32 v91, v92, v94
	v_cvt_pk_fp8_f32 v83, v93, v95
	v_cvt_pk_fp8_f32 v90, v84, v88 op_sel:[0,0,1]
	v_cvt_pk_fp8_f32 v82, v85, v89 op_sel:[0,0,1]
	s_waitcnt lgkmcnt(0)
	v_cvt_pk_fp8_f32 v91, v96, v98 op_sel:[0,0,1]
	v_cvt_pk_fp8_f32 v83, v97, v99 op_sel:[0,0,1]
	v_lshl_add_u64 v[84:85], v[78:79], 0, v[72:73]
	v_lshl_add_u64 v[78:79], v[78:79], 0, v[74:75]
	global_store_dwordx2 v[84:85], v[90:91], off
	global_store_dwordx2 v[78:79], v[82:83], off
	s_waitcnt lgkmcnt(0)
	s_and_b64 vcc, exec, s[6:7]
	s_mov_b64 s[0:1], s[4:5]
	s_waitcnt vmcnt(4)
	v_mov_b32_e32 v78, v109
	v_mov_b32_e32 v81, v108
	v_mov_b32_e32 v79, v107
	v_mov_b32_e32 v82, v106
	v_mov_b32_e32 v83, v105
	v_mov_b32_e32 v85, v104
	v_mov_b32_e32 v84, v103
	v_mov_b32_e32 v86, v80
	v_mov_b32_e32 v87, v125
	v_mov_b32_e32 v89, v124
	v_mov_b32_e32 v88, v123
	v_mov_b32_e32 v90, v122
	v_mov_b32_e32 v91, v121
	v_mov_b32_e32 v93, v120
	v_mov_b32_e32 v92, v119
	v_mov_b32_e32 v94, v118
	v_mov_b32_e32 v95, v133
	v_mov_b32_e32 v97, v132
	v_mov_b32_e32 v96, v131
	v_mov_b32_e32 v98, v130
	v_mov_b32_e32 v99, v129
	v_mov_b32_e32 v101, v128
	v_mov_b32_e32 v100, v127
	v_mov_b32_e32 v102, v126
	v_mov_b32_e32 v110, v141
	v_mov_b32_e32 v112, v140
	v_mov_b32_e32 v111, v139
	v_mov_b32_e32 v113, v138
	v_mov_b32_e32 v114, v137
	v_mov_b32_e32 v116, v136
	v_mov_b32_e32 v115, v135
	v_mov_b32_e32 v117, v134
	s_cbranch_vccnz .LBB0_1185
